# windows A/P now convert the SAME layer FFN weights (all 4 layers incl. layer 3 idle windows), B next layer; prologue layer0 stops at IT-nA-nP
# speedup vs baseline: 1.0088x; 1.0088x over previous
; #define LAS __attribute__((address_space(3)))
; __device__ __forceinline__ void convert_layer_static(const PT& a, LAS unsigned char* lds, int l, int gw, int NGW, int wave, int lane, int r_end = IT_LAYER) {
;     for (int r = 2 * gw; r < r_end; r += 2 * NGW) cv_pair(a, lds, l, r, wave, lane);
; }
; __device__ __forceinline__ void prologue_a(const PT& a, LAS unsigned char* lds) {
;     ...
;     convert_layer_static(a, lds, 0, gw, NGW, wave, lane);
;     for (int cl_ = 1; cl_ < DEPTH; ++cl_) convert_layer_static(a, lds, cl_, gw, NGW, wave, lane, CV_PRO_ITEMS);
.LBB0_22:
	s_or_saveexec_b64 s[12:13], s[0:1]
	v_lshlrev_b32_e32 v109, 1, v66
	v_readlane_b32 s0, v252, 4
	v_mul_lo_u32 v3, v12, s6
	s_lshl_b32 s17, s0, 4
	v_add_u32_e32 v115, 0, v3
	v_lshlrev_b32_e32 v111, 5, v109
	v_readlane_b32 s1, v252, 5
	s_xor_b64 exec, exec, s[12:13]
	s_cbranch_execz .LBB0_110
	v_and_b32_e32 v74, 28, v68
	v_and_b32_e32 v76, 56, v2
	v_mov_b32_e32 v79, 0
	v_lshl_add_u32 v3, v74, 2, v115
	v_mul_u32_u24_e32 v121, 0x84, v67
	v_mul_u32_u24_e32 v113, 0x84, v76
	v_lshlrev_b32_e32 v2, 2, v67
	v_mov_b32_e32 v75, v79
	v_or_b32_e32 v69, 8, v67
	v_or_b32_e32 v97, 16, v67
	v_or_b32_e32 v99, 24, v67
	v_or_b32_e32 v101, 32, v67
	v_or_b32_e32 v103, 40, v67
	v_or_b32_e32 v105, 48, v67
	v_or_b32_e32 v107, 56, v67
	v_mov_b32_e32 v77, v79
	v_add3_u32 v117, v115, v113, v2
	v_lshlrev_b32_e32 v119, 5, v109
	s_lshl_b32 s36, s17, 5
	s_mov_b64 s[18:19], 0
	s_movk_i32 s37, 0x393f
	s_movk_i32 s38, 0x453f
	s_movk_i32 s39, 0x4d3f
	s_movk_i32 s40, 0x793f
	s_movk_i32 s41, 0x15ff
	s_movk_i32 s42, 0xba3
	s_movk_i32 s43, 0x1600
	s_movk_i32 s44, 0x3ff
	s_mov_b64 s[20:21], 0xea00000
	s_mov_b32 s45, 0x478bbced
	s_movk_i32 s46, 0x9f
	s_movk_i32 s47, 0x109
	v_lshlrev_b32_e32 v78, 2, v74
	v_add_u32_e32 v123, v3, v121
	v_lshlrev_b32_e32 v80, 1, v76
	s_mov_b32 s48, 0x5f3f
	v_readlane_b32 s100, v252, 4
	s_cmp_eq_u32 s100, 0x100
	s_cselect_b32 s48, s48, 0x8f3f
	v_mov_b32_e32 v127, 0xea00
	v_mov_b32_e32 v129, 5
	v_mov_b32_e32 v130, 0x23a40
	v_mov_b32_e32 v131, 0x23a38
	v_mov_b32_e32 v132, 6
	v_mov_b32_e32 v133, 0x80
	v_mov_b32_e32 v134, 0x23a20
	v_mov_b32_e32 v135, 0x23a18
	v_mov_b32_e32 v136, 0x23a10
	v_mov_b32_e32 v137, v109
	s_branch .LBB0_25

; __device__ __forceinline__ int opaque_tid() { int t = threadIdx.x; asm volatile("" : "+v"(t)); return t; }
;     for (int it = 0; it < budget; ++it) {
;         unsigned r = 0; if (lane == 0) r = __hip_atomic_fetch_add(ctr, 2u, __ATOMIC_RELAXED, __HIP_MEMORY_SCOPE_AGENT);
;         r = (unsigned)__builtin_amdgcn_readfirstlane((int)r) + (unsigned)CV_PRO_ITEMS;
;         if (r >= (unsigned)IT_LAYER) break;
;         cv_pair(a, lds, l, (int)r, wave, lane);
;     }
; }
; __global__ void __launch_bounds__(NTHREADS, 2) mk_fwd(Args args) {
;     ...
;             if (l + 1 < DEPTH && !(G >= 256 && bid < 128)) { __syncthreads(); const int tid_ = opaque_tid(); convert_layer_queue(pt, lds, l + 1, cvq, tid_ >> 6, tid_ & 63); }
.LBB0_560:
	v_readlane_b32 s0, v252, 4
	s_cmp_lg_u32 s0, 0x100
	s_cbranch_scc1 .LcvqA_ret
	v_readlane_b32 s0, v252, 0
	v_readlane_b32 s36, v255, 0
	s_cmp_lt_u32 s0, 64
	s_cbranch_scc1 .LcvqA_ret
	s_mov_b32 s64, s36
	v_readlane_b32 s0, v254, 53
	v_readlane_b32 s1, v254, 54
	s_mov_b32 s3, s1
	s_lshl_b32 s2, s36, 6
	s_lshl_b64 s[0:1], s[2:3], 2
	v_readlane_b32 s4, v254, 60
	v_readlane_b32 s5, v254, 61
	s_add_u32 s0, s4, s0
	s_addc_u32 s1, s5, s1
	s_add_u32 s0, s0, 0x8000
	s_addc_u32 s1, s1, 0
	s_add_i32 s2, s36, 0
	s_mul_hi_u32 s33, s2, 0x2c00000
	s_mul_i32 s34, s2, 0x2c00000
	s_mul_hi_u32 s35, s2, 0x1600000
	s_mul_i32 s50, s2, 0x1600000
	s_lshl_b32 s6, s2, 11
	s_mov_b32 s7, s3
	s_lshl_b64 s[8:9], s[2:3], 24
	s_lshl_b64 s[10:11], s[2:3], 23
	s_mul_hi_u32 s51, s2, 0xc00000
	s_mul_i32 s52, s2, 0xc00000
	s_mul_hi_u32 s53, s2, 0x7280000
	s_mul_i32 s54, s2, 0x7280000
	s_mul_hi_u32 s55, s2, 0x3a00000
	v_writelane_b32 v254, s2, 53
	v_mov_b32_e32 v2, v0
	s_mul_i32 s56, s2, 0x3a00000
	v_writelane_b32 v254, s3, 54
	s_waitcnt vmcnt(0) lgkmcnt(0)
	s_barrier
	s_movk_i32 s2, 0x4200
	v_lshrrev_b32_e32 v1, 6, v2
	v_and_b32_e32 v3, 63, v2
	v_readfirstlane_b32 s100, v1
	v_readlane_b32 s101, v252, 0
	s_sub_u32 s101, s101, 64
	s_lshl_b32 s101, s101, 3
	s_add_u32 s100, s100, s101
	s_lshl_b32 s100, s100, 1
	s_add_u32 s100, s100, 0x800
	v_mul_lo_u32 v1, v1, s2
	v_cmp_eq_u32_e64 s[40:41], 0, v3
	v_add_u32_e32 v3, 0, v1
	v_lshlrev_b32_e32 v1, 2, v2
	v_and_b32_e32 v66, 28, v1
	v_bfe_u32 v1, v2, 3, 3
	v_lshlrev_b32_e32 v2, 3, v2
	v_and_b32_e32 v68, 56, v2
	v_lshl_add_u32 v4, v66, 2, v3
	v_mul_u32_u24_e32 v5, 0x84, v1
	v_mul_u32_u24_e32 v2, 0x84, v68
	v_lshlrev_b32_e32 v6, 2, v1
	v_or_b32_e32 v67, 8, v1
	v_or_b32_e32 v69, 16, v1
	v_or_b32_e32 v71, 24, v1
	v_or_b32_e32 v73, 32, v1
	v_or_b32_e32 v75, 40, v1
	v_or_b32_e32 v77, 48, v1
	v_or_b32_e32 v79, 56, v1
	v_add3_u32 v81, v3, v2, v6
	s_mov_b32 s57, 0x2
	v_add_u32_e32 v83, v4, v5
	s_branch .LcvqA_1381

; __device__ __forceinline__ int opaque_tid() { int t = threadIdx.x; asm volatile("" : "+v"(t)); return t; }
;     for (int it = 0; it < budget; ++it) {
;         unsigned r = 0; if (lane == 0) r = __hip_atomic_fetch_add(ctr, 2u, __ATOMIC_RELAXED, __HIP_MEMORY_SCOPE_AGENT);
;         r = (unsigned)__builtin_amdgcn_readfirstlane((int)r) + (unsigned)CV_PRO_ITEMS;
;         if (r >= (unsigned)IT_LAYER) break;
;         cv_pair(a, lds, l, (int)r, wave, lane);
;     }
; }
; __global__ void __launch_bounds__(NTHREADS, 2) mk_fwd(Args args) {
;     ...
;             if (l + 1 < DEPTH && !(G >= 256 && bid < 128)) { __syncthreads(); const int tid_ = opaque_tid(); convert_layer_queue(pt, lds, l + 1, cvq, tid_ >> 6, tid_ & 63); }
.LBB0_1377:
	s_cmp_eq_u32 s64, 0x63
	v_readlane_b32 s2, v253, 61
	s_cselect_b64 s[0:1], -1, 0
	v_readlane_b32 s3, v253, 62
	s_or_b64 s[0:1], s[2:3], s[0:1]
	v_readlane_b32 s2, v252, 4
	s_cmp_lg_u32 s2, 0x100
	s_cselect_b64 s[2:3], -1, 0
	s_or_b64 s[0:1], s[0:1], s[2:3]
	v_readlane_b32 s28, v254, 55
	s_mov_b32 s36, s64
	s_and_b64 vcc, exec, s[0:1]
	v_readlane_b32 s29, v254, 56
	s_cbranch_vccnz .LBB0_1470
	v_readlane_b32 s0, v254, 53
	v_readlane_b32 s1, v254, 54
	s_mov_b32 s3, s1
	s_lshl_b32 s2, s36, 6
	s_lshl_b64 s[0:1], s[2:3], 2
	v_readlane_b32 s4, v254, 60
	v_readlane_b32 s5, v254, 61
	s_add_u32 s0, s4, s0
	s_addc_u32 s1, s5, s1
	s_add_u32 s0, s0, 0x8000
	s_addc_u32 s1, s1, 0
	s_add_i32 s2, s36, 0
	s_mul_hi_u32 s33, s2, 0x2c00000
	s_mul_i32 s34, s2, 0x2c00000
	s_mul_hi_u32 s35, s2, 0x1600000
	s_mul_i32 s50, s2, 0x1600000
	s_lshl_b32 s6, s2, 11
	s_mov_b32 s7, s3
	s_lshl_b64 s[8:9], s[2:3], 24
	s_lshl_b64 s[10:11], s[2:3], 23
	s_mul_hi_u32 s51, s2, 0xc00000
	s_mul_i32 s52, s2, 0xc00000
	s_mul_hi_u32 s53, s2, 0x7280000
	s_mul_i32 s54, s2, 0x7280000
	s_mul_hi_u32 s55, s2, 0x3a00000
	v_writelane_b32 v254, s2, 53
	v_mov_b32_e32 v2, v0
	s_mul_i32 s56, s2, 0x3a00000
	v_writelane_b32 v254, s3, 54
	s_waitcnt vmcnt(0) lgkmcnt(0)
	s_barrier
	s_movk_i32 s2, 0x4200
	v_lshrrev_b32_e32 v1, 6, v2
	v_and_b32_e32 v3, 63, v2
	v_readfirstlane_b32 s100, v1
	v_readlane_b32 s101, v252, 0
	s_sub_u32 s101, s101, 128
	s_lshl_b32 s101, s101, 3
	s_add_u32 s100, s100, s101
	s_lshl_b32 s100, s100, 1
	s_add_u32 s100, s100, 0x2000
	v_mul_lo_u32 v1, v1, s2
	v_cmp_eq_u32_e64 s[40:41], 0, v3
	v_add_u32_e32 v3, 0, v1
	v_lshlrev_b32_e32 v1, 2, v2
	v_and_b32_e32 v66, 28, v1
	v_bfe_u32 v1, v2, 3, 3
	v_lshlrev_b32_e32 v2, 3, v2
	v_and_b32_e32 v68, 56, v2
	v_lshl_add_u32 v4, v66, 2, v3
	v_mul_u32_u24_e32 v5, 0x84, v1
	v_mul_u32_u24_e32 v2, 0x84, v68
	v_lshlrev_b32_e32 v6, 2, v1
	v_or_b32_e32 v67, 8, v1
	v_or_b32_e32 v69, 16, v1
	v_or_b32_e32 v71, 24, v1
	v_or_b32_e32 v73, 32, v1
	v_or_b32_e32 v75, 40, v1
	v_or_b32_e32 v77, 48, v1
	v_or_b32_e32 v79, 56, v1
	v_add3_u32 v81, v3, v2, v6
	s_mov_b32 s57, 0x3
	v_add_u32_e32 v83, v4, v5
	s_branch .LBB0_1381

; __device__ __forceinline__ int opaque_tid() { int t = threadIdx.x; asm volatile("" : "+v"(t)); return t; }
;     for (int it = 0; it < budget; ++it) {
;         unsigned r = 0; if (lane == 0) r = __hip_atomic_fetch_add(ctr, 2u, __ATOMIC_RELAXED, __HIP_MEMORY_SCOPE_AGENT);
;         r = (unsigned)__builtin_amdgcn_readfirstlane((int)r) + (unsigned)CV_PRO_ITEMS;
;         if (r >= (unsigned)IT_LAYER) break;
;         cv_pair(a, lds, l, (int)r, wave, lane);
;     }
; }
; __global__ void __launch_bounds__(NTHREADS, 2) mk_fwd(Args args) {
;     ...
;             if (l + 1 < DEPTH && !(G >= 256 && bid < 128)) { __syncthreads(); const int tid_ = opaque_tid(); convert_layer_queue(pt, lds, l + 1, cvq, tid_ >> 6, tid_ & 63); }
.LBB0_1843:
	v_readlane_b32 s2, v252, 4
	s_cmp_lg_u32 s2, 0x100
	s_cbranch_scc1 .LcvqB_skip
	v_readlane_b32 s2, v252, 0
	s_cmp_lt_u32 s2, 128
	s_cbranch_scc1 .LcvqB_skip
	s_cmp_gt_u32 s36, 2
	s_cbranch_scc1 .LcvqB_skip
	v_writelane_b32 v255, s0, 8
	v_writelane_b32 v255, s1, 9
	v_writelane_b32 v255, s40, 10
	v_writelane_b32 v255, s41, 11
	s_mov_b32 s64, s36
	v_readlane_b32 s0, v254, 53
	v_readlane_b32 s1, v254, 54
	s_mov_b32 s3, s1
	s_lshl_b32 s2, s36, 6
	s_lshl_b64 s[0:1], s[2:3], 2
	v_readlane_b32 s4, v254, 60
	v_readlane_b32 s5, v254, 61
	s_add_u32 s0, s4, s0
	s_addc_u32 s1, s5, s1
	s_add_u32 s0, s0, 0x8000
	s_addc_u32 s1, s1, 0
	s_add_i32 s2, s36, 1
	s_mul_hi_u32 s33, s2, 0x2c00000
	s_mul_i32 s34, s2, 0x2c00000
	s_mul_hi_u32 s35, s2, 0x1600000
	s_mul_i32 s50, s2, 0x1600000
	s_lshl_b32 s6, s2, 11
	s_mov_b32 s7, s3
	s_lshl_b64 s[8:9], s[2:3], 24
	s_lshl_b64 s[10:11], s[2:3], 23
	s_mul_hi_u32 s51, s2, 0xc00000
	s_mul_i32 s52, s2, 0xc00000
	s_mul_hi_u32 s53, s2, 0x7280000
	s_mul_i32 s54, s2, 0x7280000
	s_mul_hi_u32 s55, s2, 0x3a00000
	v_writelane_b32 v254, s2, 53
	v_mov_b32_e32 v2, v0
	s_mul_i32 s56, s2, 0x3a00000
	v_writelane_b32 v254, s3, 54
	s_waitcnt vmcnt(0) lgkmcnt(0)
	s_barrier
	s_movk_i32 s2, 0x4200
	v_lshrrev_b32_e32 v1, 6, v2
	v_and_b32_e32 v3, 63, v2
	v_readfirstlane_b32 s100, v1
	v_readlane_b32 s101, v252, 0
	s_sub_u32 s101, s101, 128
	s_lshl_b32 s101, s101, 3
	s_add_u32 s100, s100, s101
	s_lshl_b32 s100, s100, 1
	s_add_u32 s100, s100, 0x0
	v_mul_lo_u32 v1, v1, s2
	v_cmp_eq_u32_e64 s[40:41], 0, v3
	v_add_u32_e32 v3, 0, v1
	v_lshlrev_b32_e32 v1, 2, v2
	v_and_b32_e32 v66, 28, v1
	v_bfe_u32 v1, v2, 3, 3
	v_lshlrev_b32_e32 v2, 3, v2
	v_and_b32_e32 v68, 56, v2
	v_lshl_add_u32 v4, v66, 2, v3
	v_mul_u32_u24_e32 v5, 0x84, v1
	v_mul_u32_u24_e32 v2, 0x84, v68
	v_lshlrev_b32_e32 v6, 2, v1
	v_or_b32_e32 v67, 8, v1
	v_or_b32_e32 v69, 16, v1
	v_or_b32_e32 v71, 24, v1
	v_or_b32_e32 v73, 32, v1
	v_or_b32_e32 v75, 40, v1
	v_or_b32_e32 v77, 48, v1
	v_or_b32_e32 v79, 56, v1
	v_add3_u32 v81, v3, v2, v6
	s_mov_b32 s57, 0x1
	v_add_u32_e32 v83, v4, v5
	s_branch .LcvqB_1381
